# as v8 plus FFN2-in (P13) loop fragment registers renamed: srcA 0 mod 4, srcB k0 0 / k1 2 mod 4
# baseline (speedup 1.0000x reference)
.LBB0_1644:
	ds_read_b128 v[220:223], v149
	ds_read_b128 v[216:219], v149 offset:1024
	ds_read_b128 v[212:215], v149 offset:2048
	ds_read_b128 v[208:211], v149 offset:3072
	ds_read_b128 v[200:203], v150
	ds_read_b128 v[196:199], v150 offset:1024
	ds_read_b128 v[192:195], v150 offset:2048
	ds_read_b128 v[188:191], v150 offset:3072
	s_add_u32 s28, s26, 0xfff00080
	s_addc_u32 s29, s27, -1
	s_cmp_eq_u32 s55, 60
	s_cselect_b32 s31, s17, s29
	s_cselect_b32 s30, s51, s28
	s_cselect_b32 s29, s15, s54
	s_cselect_b32 s28, s52, s53
	v_lshl_add_u64 v[144:145], s[26:27], 0, v[140:141]
	s_add_i32 m0, s25, 0xc000
	ds_read_b128 v[184:187], v151
	ds_read_b128 v[154:157], v151 offset:1024
	ds_read_b128 v[180:183], v151 offset:2048
	ds_read_b128 v[158:161], v151 offset:3072
	ds_read_b128 v[176:179], v151 offset:4096
	ds_read_b128 v[162:165], v151 offset:5120
	ds_read_b128 v[172:175], v151 offset:6144
	ds_read_b128 v[166:169], v151 offset:7168
	global_load_lds_dwordx4 v[144:145], off
	v_lshl_add_u64 v[144:145], s[26:27], 0, v[142:143]
	s_add_i32 m0, s25, 0xe000
	s_nop 0
	global_load_lds_dwordx4 v[144:145], off
	s_waitcnt vmcnt(8)
	s_waitcnt lgkmcnt(0)
	s_barrier
	s_setprio 1
	s_waitcnt lgkmcnt(0)
	v_mfma_f32_16x16x32_bf16 v[126:129], v[220:223], v[184:187], v[126:129]
	v_mfma_f32_16x16x32_bf16 v[126:129], v[216:219], v[154:157], v[126:129]
	v_mfma_f32_16x16x32_bf16 v[122:125], v[212:215], v[184:187], v[122:125]
	v_mfma_f32_16x16x32_bf16 v[122:125], v[208:211], v[154:157], v[122:125]
	v_mfma_f32_16x16x32_bf16 v[106:109], v[212:215], v[180:183], v[106:109]
	v_mfma_f32_16x16x32_bf16 v[106:109], v[208:211], v[158:161], v[106:109]
	v_mfma_f32_16x16x32_bf16 v[110:113], v[220:223], v[180:183], v[110:113]
	v_mfma_f32_16x16x32_bf16 v[110:113], v[216:219], v[158:161], v[110:113]
	v_mfma_f32_16x16x32_bf16 v[98:101], v[220:223], v[176:179], v[98:101]
	v_mfma_f32_16x16x32_bf16 v[98:101], v[216:219], v[162:165], v[98:101]
	v_mfma_f32_16x16x32_bf16 v[90:93], v[212:215], v[176:179], v[90:93]
	v_mfma_f32_16x16x32_bf16 v[90:93], v[208:211], v[162:165], v[90:93]
	v_mfma_f32_16x16x32_bf16 v[74:77], v[212:215], v[172:175], v[74:77]
	v_mfma_f32_16x16x32_bf16 v[74:77], v[208:211], v[166:169], v[74:77]
	v_mfma_f32_16x16x32_bf16 v[82:85], v[220:223], v[172:175], v[82:85]
	v_mfma_f32_16x16x32_bf16 v[82:85], v[216:219], v[166:169], v[82:85]
	v_mfma_f32_16x16x32_bf16 v[118:121], v[200:203], v[184:187], v[118:121]
	v_mfma_f32_16x16x32_bf16 v[118:121], v[196:199], v[154:157], v[118:121]
	v_mfma_f32_16x16x32_bf16 v[114:117], v[192:195], v[184:187], v[114:117]
	v_mfma_f32_16x16x32_bf16 v[114:117], v[188:191], v[154:157], v[114:117]
	v_mfma_f32_16x16x32_bf16 v[94:97], v[192:195], v[180:183], v[94:97]
	v_mfma_f32_16x16x32_bf16 v[94:97], v[188:191], v[158:161], v[94:97]
	v_mfma_f32_16x16x32_bf16 v[102:105], v[200:203], v[180:183], v[102:105]
	v_mfma_f32_16x16x32_bf16 v[102:105], v[196:199], v[158:161], v[102:105]
	v_mfma_f32_16x16x32_bf16 v[86:89], v[200:203], v[176:179], v[86:89]
	v_mfma_f32_16x16x32_bf16 v[86:89], v[196:199], v[162:165], v[86:89]
	v_mfma_f32_16x16x32_bf16 v[78:81], v[192:195], v[176:179], v[78:81]
	v_mfma_f32_16x16x32_bf16 v[78:81], v[188:191], v[162:165], v[78:81]
	v_mfma_f32_16x16x32_bf16 v[66:69], v[192:195], v[172:175], v[66:69]
	v_mfma_f32_16x16x32_bf16 v[66:69], v[188:191], v[166:169], v[66:69]
	v_mfma_f32_16x16x32_bf16 v[70:73], v[200:203], v[172:175], v[70:73]
	v_mfma_f32_16x16x32_bf16 v[70:73], v[196:199], v[166:169], v[70:73]
	s_setprio 0
	s_barrier
	s_add_i32 s56, s48, s13
	v_lshl_add_u64 v[144:145], s[28:29], 0, v[132:133]
	s_mov_b32 m0, s56
	ds_read_b128 v[184:187], v151 offset:16384
	ds_read_b128 v[154:157], v151 offset:17408
	ds_read_b128 v[180:183], v151 offset:18432
	ds_read_b128 v[158:161], v151 offset:19456
	ds_read_b128 v[176:179], v151 offset:20480
	ds_read_b128 v[162:165], v151 offset:21504
	ds_read_b128 v[172:175], v151 offset:22528
	ds_read_b128 v[166:169], v151 offset:23552
	global_load_lds_dwordx4 v[144:145], off
	s_add_i32 m0, s56, 0x2000
	s_add_u32 s56, s28, 0x100000
	v_lshl_add_u64 v[152:153], s[28:29], 0, v[136:137]
	s_addc_u32 s57, s29, 0
	s_add_i32 s58, s49, s13
	global_load_lds_dwordx4 v[152:153], off
	v_lshl_add_u64 v[170:171], s[56:57], 0, v[132:133]
	s_mov_b32 m0, s58
	v_lshl_add_u64 v[206:207], s[30:31], 0, v[134:135]
	global_load_lds_dwordx4 v[170:171], off
	v_lshl_add_u64 v[170:171], s[56:57], 0, v[136:137]
	s_add_i32 m0, s58, 0x2000
	s_nop 0
	global_load_lds_dwordx4 v[170:171], off
	v_lshl_add_u64 v[170:171], s[30:31], 0, v[130:131]
	s_mov_b32 m0, s25
	s_nop 0
	global_load_lds_dwordx4 v[170:171], off
	s_mov_b32 m0, s39
	s_nop 0
	global_load_lds_dwordx4 v[206:207], off
	s_waitcnt vmcnt(8)
	s_waitcnt lgkmcnt(0)
	s_barrier
	s_setprio 1
	s_waitcnt lgkmcnt(0)
	v_mfma_f32_16x16x32_bf16 v[62:65], v[220:223], v[184:187], v[62:65]
	v_mfma_f32_16x16x32_bf16 v[62:65], v[216:219], v[154:157], v[62:65]
	v_mfma_f32_16x16x32_bf16 v[58:61], v[212:215], v[184:187], v[58:61]
	v_mfma_f32_16x16x32_bf16 v[58:61], v[208:211], v[154:157], v[58:61]
	v_mfma_f32_16x16x32_bf16 v[42:45], v[212:215], v[180:183], v[42:45]
	v_mfma_f32_16x16x32_bf16 v[42:45], v[208:211], v[158:161], v[42:45]
	v_mfma_f32_16x16x32_bf16 v[50:53], v[220:223], v[180:183], v[50:53]
	v_mfma_f32_16x16x32_bf16 v[50:53], v[216:219], v[158:161], v[50:53]
	v_mfma_f32_16x16x32_bf16 v[34:37], v[220:223], v[176:179], v[34:37]
	v_mfma_f32_16x16x32_bf16 v[34:37], v[216:219], v[162:165], v[34:37]
	v_mfma_f32_16x16x32_bf16 v[26:29], v[212:215], v[176:179], v[26:29]
	v_mfma_f32_16x16x32_bf16 v[26:29], v[208:211], v[162:165], v[26:29]
	v_mfma_f32_16x16x32_bf16 v[10:13], v[212:215], v[172:175], v[10:13]
	v_mfma_f32_16x16x32_bf16 v[10:13], v[208:211], v[166:169], v[10:13]
	v_mfma_f32_16x16x32_bf16 v[14:17], v[220:223], v[172:175], v[14:17]
	v_mfma_f32_16x16x32_bf16 v[14:17], v[216:219], v[166:169], v[14:17]
	v_mfma_f32_16x16x32_bf16 v[54:57], v[200:203], v[184:187], v[54:57]
	v_mfma_f32_16x16x32_bf16 v[54:57], v[196:199], v[154:157], v[54:57]
	v_mfma_f32_16x16x32_bf16 v[46:49], v[192:195], v[184:187], v[46:49]
	v_mfma_f32_16x16x32_bf16 v[46:49], v[188:191], v[154:157], v[46:49]
	v_mfma_f32_16x16x32_bf16 v[30:33], v[192:195], v[180:183], v[30:33]
	v_mfma_f32_16x16x32_bf16 v[30:33], v[188:191], v[158:161], v[30:33]
	v_mfma_f32_16x16x32_bf16 v[38:41], v[200:203], v[180:183], v[38:41]
	v_mfma_f32_16x16x32_bf16 v[38:41], v[196:199], v[158:161], v[38:41]
	v_mfma_f32_16x16x32_bf16 v[22:25], v[200:203], v[176:179], v[22:25]
	v_mfma_f32_16x16x32_bf16 v[22:25], v[196:199], v[162:165], v[22:25]
	v_mfma_f32_16x16x32_bf16 v[18:21], v[192:195], v[176:179], v[18:21]
	v_mfma_f32_16x16x32_bf16 v[18:21], v[188:191], v[162:165], v[18:21]
	v_mfma_f32_16x16x32_bf16 v[2:5], v[192:195], v[172:175], v[2:5]
	v_mfma_f32_16x16x32_bf16 v[2:5], v[188:191], v[166:169], v[2:5]
	v_mfma_f32_16x16x32_bf16 v[6:9], v[200:203], v[172:175], v[6:9]
	v_mfma_f32_16x16x32_bf16 v[6:9], v[196:199], v[166:169], v[6:9]
	s_setprio 0
	s_barrier
	s_add_i32 s56, 0, 0x18000
	s_add_i32 s57, 0, 0x1c000
	v_add_u32_e32 v208, s56, v147
	v_add_u32_e32 v188, s57, v147
	ds_read_b128 v[220:223], v208
	ds_read_b128 v[216:219], v208 offset:1024
	ds_read_b128 v[212:215], v208 offset:2048
	ds_read_b128 v[208:211], v208 offset:3072
	ds_read_b128 v[200:203], v188
	ds_read_b128 v[196:199], v188 offset:1024
	ds_read_b128 v[192:195], v188 offset:2048
	ds_read_b128 v[188:191], v188 offset:3072
	s_add_u32 s30, s30, 0x100000
	s_addc_u32 s31, s31, 0
	s_mov_b32 m0, s40
	v_lshl_add_u64 v[224:225], s[30:31], 0, v[130:131]
	ds_read_b128 v[184:187], v151 offset:32768
	ds_read_b128 v[154:157], v151 offset:33792
	ds_read_b128 v[180:183], v151 offset:34816
	ds_read_b128 v[158:161], v151 offset:35840
	ds_read_b128 v[176:179], v151 offset:36864
	ds_read_b128 v[162:165], v151 offset:37888
	ds_read_b128 v[172:175], v151 offset:38912
	ds_read_b128 v[166:169], v151 offset:39936
	global_load_lds_dwordx4 v[224:225], off
	v_lshl_add_u64 v[224:225], s[30:31], 0, v[134:135]
	s_mov_b32 m0, s41
	s_nop 0
	global_load_lds_dwordx4 v[224:225], off
	s_waitcnt vmcnt(8)
	s_waitcnt lgkmcnt(0)
	s_barrier
	s_setprio 1
	s_waitcnt lgkmcnt(0)
	v_mfma_f32_16x16x32_bf16 v[126:129], v[220:223], v[184:187], v[126:129]
	v_mfma_f32_16x16x32_bf16 v[126:129], v[216:219], v[154:157], v[126:129]
	v_mfma_f32_16x16x32_bf16 v[122:125], v[212:215], v[184:187], v[122:125]
	v_mfma_f32_16x16x32_bf16 v[122:125], v[208:211], v[154:157], v[122:125]
	v_mfma_f32_16x16x32_bf16 v[106:109], v[212:215], v[180:183], v[106:109]
	v_mfma_f32_16x16x32_bf16 v[106:109], v[208:211], v[158:161], v[106:109]
	v_mfma_f32_16x16x32_bf16 v[110:113], v[220:223], v[180:183], v[110:113]
	v_mfma_f32_16x16x32_bf16 v[110:113], v[216:219], v[158:161], v[110:113]
	v_mfma_f32_16x16x32_bf16 v[98:101], v[220:223], v[176:179], v[98:101]
	v_mfma_f32_16x16x32_bf16 v[98:101], v[216:219], v[162:165], v[98:101]
	v_mfma_f32_16x16x32_bf16 v[90:93], v[212:215], v[176:179], v[90:93]
	v_mfma_f32_16x16x32_bf16 v[90:93], v[208:211], v[162:165], v[90:93]
	v_mfma_f32_16x16x32_bf16 v[74:77], v[212:215], v[172:175], v[74:77]
	v_mfma_f32_16x16x32_bf16 v[74:77], v[208:211], v[166:169], v[74:77]
	v_mfma_f32_16x16x32_bf16 v[82:85], v[220:223], v[172:175], v[82:85]
	v_mfma_f32_16x16x32_bf16 v[82:85], v[216:219], v[166:169], v[82:85]
	v_mfma_f32_16x16x32_bf16 v[118:121], v[200:203], v[184:187], v[118:121]
	v_mfma_f32_16x16x32_bf16 v[118:121], v[196:199], v[154:157], v[118:121]
	v_mfma_f32_16x16x32_bf16 v[114:117], v[192:195], v[184:187], v[114:117]
	v_mfma_f32_16x16x32_bf16 v[114:117], v[188:191], v[154:157], v[114:117]
	v_mfma_f32_16x16x32_bf16 v[94:97], v[192:195], v[180:183], v[94:97]
	v_mfma_f32_16x16x32_bf16 v[94:97], v[188:191], v[158:161], v[94:97]
	v_mfma_f32_16x16x32_bf16 v[102:105], v[200:203], v[180:183], v[102:105]
	v_mfma_f32_16x16x32_bf16 v[102:105], v[196:199], v[158:161], v[102:105]
	v_mfma_f32_16x16x32_bf16 v[86:89], v[200:203], v[176:179], v[86:89]
	v_mfma_f32_16x16x32_bf16 v[86:89], v[196:199], v[162:165], v[86:89]
	v_mfma_f32_16x16x32_bf16 v[78:81], v[192:195], v[176:179], v[78:81]
	v_mfma_f32_16x16x32_bf16 v[78:81], v[188:191], v[162:165], v[78:81]
	v_mfma_f32_16x16x32_bf16 v[66:69], v[192:195], v[172:175], v[66:69]
	v_mfma_f32_16x16x32_bf16 v[66:69], v[188:191], v[166:169], v[66:69]
	v_mfma_f32_16x16x32_bf16 v[70:73], v[200:203], v[172:175], v[70:73]
	v_mfma_f32_16x16x32_bf16 v[70:73], v[196:199], v[166:169], v[70:73]
	s_setprio 0
	s_barrier
	s_add_i32 s30, s56, s13
	v_lshl_add_u64 v[144:145], v[144:145], 0, s[8:9]
	s_mov_b32 m0, s30
	ds_read_b128 v[184:187], v151 offset:49152
	ds_read_b128 v[154:157], v151 offset:50176
	ds_read_b128 v[180:183], v151 offset:51200
	ds_read_b128 v[158:161], v151 offset:52224
	ds_read_b128 v[176:179], v151 offset:53248
	ds_read_b128 v[162:165], v151 offset:54272
	ds_read_b128 v[172:175], v151 offset:55296
	ds_read_b128 v[166:169], v151 offset:56320
	global_load_lds_dwordx4 v[144:145], off
	s_add_i32 m0, s30, 0x2000
	s_add_u32 s28, s28, 0x100080
	v_lshl_add_u64 v[144:145], v[152:153], 0, s[8:9]
	s_addc_u32 s29, s29, 0
	s_add_i32 s30, s57, s13
	global_load_lds_dwordx4 v[144:145], off
	v_lshl_add_u64 v[144:145], s[28:29], 0, v[132:133]
	s_mov_b32 m0, s30
	s_nop 0
	global_load_lds_dwordx4 v[144:145], off
	v_lshl_add_u64 v[144:145], s[28:29], 0, v[136:137]
	s_add_i32 m0, s30, 0x2000
	s_nop 0
	global_load_lds_dwordx4 v[144:145], off
	v_lshl_add_u64 v[144:145], v[170:171], 0, s[8:9]
	s_mov_b32 m0, s42
	s_nop 0
	global_load_lds_dwordx4 v[144:145], off
	v_lshl_add_u64 v[144:145], v[206:207], 0, s[8:9]
	s_mov_b32 m0, s43
	s_nop 0
	global_load_lds_dwordx4 v[144:145], off
	s_waitcnt vmcnt(8)
	s_waitcnt lgkmcnt(0)
	s_barrier
	s_setprio 1
	s_waitcnt lgkmcnt(0)
	v_mfma_f32_16x16x32_bf16 v[62:65], v[220:223], v[184:187], v[62:65]
	v_mfma_f32_16x16x32_bf16 v[62:65], v[216:219], v[154:157], v[62:65]
	v_mfma_f32_16x16x32_bf16 v[58:61], v[212:215], v[184:187], v[58:61]
	v_mfma_f32_16x16x32_bf16 v[58:61], v[208:211], v[154:157], v[58:61]
	v_mfma_f32_16x16x32_bf16 v[42:45], v[212:215], v[180:183], v[42:45]
	v_mfma_f32_16x16x32_bf16 v[42:45], v[208:211], v[158:161], v[42:45]
	v_mfma_f32_16x16x32_bf16 v[50:53], v[220:223], v[180:183], v[50:53]
	v_mfma_f32_16x16x32_bf16 v[50:53], v[216:219], v[158:161], v[50:53]
	v_mfma_f32_16x16x32_bf16 v[34:37], v[220:223], v[176:179], v[34:37]
	v_mfma_f32_16x16x32_bf16 v[34:37], v[216:219], v[162:165], v[34:37]
	v_mfma_f32_16x16x32_bf16 v[26:29], v[212:215], v[176:179], v[26:29]
	v_mfma_f32_16x16x32_bf16 v[26:29], v[208:211], v[162:165], v[26:29]
	v_mfma_f32_16x16x32_bf16 v[10:13], v[212:215], v[172:175], v[10:13]
	v_mfma_f32_16x16x32_bf16 v[10:13], v[208:211], v[166:169], v[10:13]
	v_mfma_f32_16x16x32_bf16 v[14:17], v[220:223], v[172:175], v[14:17]
	v_mfma_f32_16x16x32_bf16 v[14:17], v[216:219], v[166:169], v[14:17]
	v_mfma_f32_16x16x32_bf16 v[54:57], v[200:203], v[184:187], v[54:57]
	v_mfma_f32_16x16x32_bf16 v[54:57], v[196:199], v[154:157], v[54:57]
	v_mfma_f32_16x16x32_bf16 v[46:49], v[192:195], v[184:187], v[46:49]
	v_mfma_f32_16x16x32_bf16 v[46:49], v[188:191], v[154:157], v[46:49]
	v_mfma_f32_16x16x32_bf16 v[30:33], v[192:195], v[180:183], v[30:33]
	v_mfma_f32_16x16x32_bf16 v[30:33], v[188:191], v[158:161], v[30:33]
	v_mfma_f32_16x16x32_bf16 v[38:41], v[200:203], v[180:183], v[38:41]
	v_mfma_f32_16x16x32_bf16 v[38:41], v[196:199], v[158:161], v[38:41]
	v_mfma_f32_16x16x32_bf16 v[22:25], v[200:203], v[176:179], v[22:25]
	v_mfma_f32_16x16x32_bf16 v[22:25], v[196:199], v[162:165], v[22:25]
	v_mfma_f32_16x16x32_bf16 v[18:21], v[192:195], v[176:179], v[18:21]
	v_mfma_f32_16x16x32_bf16 v[18:21], v[188:191], v[162:165], v[18:21]
	v_mfma_f32_16x16x32_bf16 v[2:5], v[192:195], v[172:175], v[2:5]
	v_mfma_f32_16x16x32_bf16 v[2:5], v[188:191], v[166:169], v[2:5]
	v_mfma_f32_16x16x32_bf16 v[6:9], v[200:203], v[172:175], v[6:9]
	v_mfma_f32_16x16x32_bf16 v[6:9], v[196:199], v[166:169], v[6:9]
	s_setprio 0
	s_barrier
	s_add_i32 s55, s55, 2
	s_add_u32 s26, s26, 0x100
	s_addc_u32 s27, s27, 0
	s_add_u32 s53, s53, 0x100
	s_addc_u32 s54, s54, 0
	s_cmp_gt_u32 s55, 61
	s_cbranch_scc0 .LBB0_1644
	s_and_b64 vcc, exec, s[10:11]
	s_cbranch_vccz .LBB0_1647
	s_barrier
